# scan0-phase mod_partials(1): 64 loads in flight + v_readlane broadcasts instead of ds_bpermute
# baseline (speedup 1.0000x reference)
.LBB0_931:
	v_add_co_u32_e32 v12, vcc, 0xc00000, v12
	s_nop 1
	v_addc_co_u32_e32 v13, vcc, 0, v13, vcc
	global_load_dword v132, v[12:13], off nt
	v_add_co_u32_e32 v12, vcc, 0x3000, v12
	s_nop 1
	v_addc_co_u32_e32 v13, vcc, 0, v13, vcc
	global_load_dword v133, v[12:13], off nt
	v_add_co_u32_e32 v12, vcc, 0x3000, v12
	s_nop 1
	v_addc_co_u32_e32 v13, vcc, 0, v13, vcc
	global_load_dword v134, v[12:13], off nt
	v_add_co_u32_e32 v12, vcc, 0x3000, v12
	s_nop 1
	v_addc_co_u32_e32 v13, vcc, 0, v13, vcc
	global_load_dword v135, v[12:13], off nt
	v_add_co_u32_e32 v12, vcc, 0x3000, v12
	s_nop 1
	v_addc_co_u32_e32 v13, vcc, 0, v13, vcc
	global_load_dword v136, v[12:13], off nt
	v_add_co_u32_e32 v12, vcc, 0x3000, v12
	s_nop 1
	v_addc_co_u32_e32 v13, vcc, 0, v13, vcc
	global_load_dword v137, v[12:13], off nt
	v_add_co_u32_e32 v12, vcc, 0x3000, v12
	s_nop 1
	v_addc_co_u32_e32 v13, vcc, 0, v13, vcc
	global_load_dword v138, v[12:13], off nt
	v_add_co_u32_e32 v12, vcc, 0x3000, v12
	s_nop 1
	v_addc_co_u32_e32 v13, vcc, 0, v13, vcc
	global_load_dword v139, v[12:13], off nt
	v_add_co_u32_e32 v12, vcc, 0x3000, v12
	s_nop 1
	v_addc_co_u32_e32 v13, vcc, 0, v13, vcc
	global_load_dword v140, v[12:13], off nt
	v_add_co_u32_e32 v12, vcc, 0x3000, v12
	s_nop 1
	v_addc_co_u32_e32 v13, vcc, 0, v13, vcc
	global_load_dword v141, v[12:13], off nt
	v_add_co_u32_e32 v12, vcc, 0x3000, v12
	s_nop 1
	v_addc_co_u32_e32 v13, vcc, 0, v13, vcc
	global_load_dword v142, v[12:13], off nt
	v_add_co_u32_e32 v12, vcc, 0x3000, v12
	s_nop 1
	v_addc_co_u32_e32 v13, vcc, 0, v13, vcc
	global_load_dword v143, v[12:13], off nt
	v_add_co_u32_e32 v12, vcc, 0x3000, v12
	s_nop 1
	v_addc_co_u32_e32 v13, vcc, 0, v13, vcc
	global_load_dword v144, v[12:13], off nt
	v_add_co_u32_e32 v12, vcc, 0x3000, v12
	s_nop 1
	v_addc_co_u32_e32 v13, vcc, 0, v13, vcc
	global_load_dword v145, v[12:13], off nt
	v_add_co_u32_e32 v12, vcc, 0x3000, v12
	s_nop 1
	v_addc_co_u32_e32 v13, vcc, 0, v13, vcc
	global_load_dword v146, v[12:13], off nt
	v_add_co_u32_e32 v12, vcc, 0x3000, v12
	s_nop 1
	v_addc_co_u32_e32 v13, vcc, 0, v13, vcc
	global_load_dword v147, v[12:13], off nt
	v_add_co_u32_e32 v12, vcc, 0x3000, v12
	s_nop 1
	v_addc_co_u32_e32 v13, vcc, 0, v13, vcc
	global_load_dword v148, v[12:13], off nt
	v_add_co_u32_e32 v12, vcc, 0x3000, v12
	s_nop 1
	v_addc_co_u32_e32 v13, vcc, 0, v13, vcc
	global_load_dword v149, v[12:13], off nt
	v_add_co_u32_e32 v12, vcc, 0x3000, v12
	s_nop 1
	v_addc_co_u32_e32 v13, vcc, 0, v13, vcc
	global_load_dword v150, v[12:13], off nt
	v_add_co_u32_e32 v12, vcc, 0x3000, v12
	s_nop 1
	v_addc_co_u32_e32 v13, vcc, 0, v13, vcc
	global_load_dword v151, v[12:13], off nt
	v_add_co_u32_e32 v12, vcc, 0x3000, v12
	s_nop 1
	v_addc_co_u32_e32 v13, vcc, 0, v13, vcc
	global_load_dword v152, v[12:13], off nt
	v_add_co_u32_e32 v12, vcc, 0x3000, v12
	s_nop 1
	v_addc_co_u32_e32 v13, vcc, 0, v13, vcc
	global_load_dword v153, v[12:13], off nt
	v_add_co_u32_e32 v12, vcc, 0x3000, v12
	s_nop 1
	v_addc_co_u32_e32 v13, vcc, 0, v13, vcc
	global_load_dword v154, v[12:13], off nt
	v_add_co_u32_e32 v12, vcc, 0x3000, v12
	s_nop 1
	v_addc_co_u32_e32 v13, vcc, 0, v13, vcc
	global_load_dword v155, v[12:13], off nt
	v_add_co_u32_e32 v12, vcc, 0x3000, v12
	s_nop 1
	v_addc_co_u32_e32 v13, vcc, 0, v13, vcc
	global_load_dword v156, v[12:13], off nt
	v_add_co_u32_e32 v12, vcc, 0x3000, v12
	s_nop 1
	v_addc_co_u32_e32 v13, vcc, 0, v13, vcc
	global_load_dword v157, v[12:13], off nt
	v_add_co_u32_e32 v12, vcc, 0x3000, v12
	s_nop 1
	v_addc_co_u32_e32 v13, vcc, 0, v13, vcc
	global_load_dword v158, v[12:13], off nt
	v_add_co_u32_e32 v12, vcc, 0x3000, v12
	s_nop 1
	v_addc_co_u32_e32 v13, vcc, 0, v13, vcc
	global_load_dword v159, v[12:13], off nt
	v_add_co_u32_e32 v12, vcc, 0x3000, v12
	s_nop 1
	v_addc_co_u32_e32 v13, vcc, 0, v13, vcc
	global_load_dword v160, v[12:13], off nt
	v_add_co_u32_e32 v12, vcc, 0x3000, v12
	s_nop 1
	v_addc_co_u32_e32 v13, vcc, 0, v13, vcc
	global_load_dword v161, v[12:13], off nt
	v_add_co_u32_e32 v12, vcc, 0x3000, v12
	s_nop 1
	v_addc_co_u32_e32 v13, vcc, 0, v13, vcc
	global_load_dword v162, v[12:13], off nt
	v_add_co_u32_e32 v12, vcc, 0x3000, v12
	s_nop 1
	v_addc_co_u32_e32 v13, vcc, 0, v13, vcc
	global_load_dword v163, v[12:13], off nt
	v_add_co_u32_e32 v12, vcc, 0x3000, v12
	s_nop 1
	v_addc_co_u32_e32 v13, vcc, 0, v13, vcc
	global_load_dword v164, v[12:13], off nt
	v_add_co_u32_e32 v12, vcc, 0x3000, v12
	s_nop 1
	v_addc_co_u32_e32 v13, vcc, 0, v13, vcc
	global_load_dword v165, v[12:13], off nt
	v_add_co_u32_e32 v12, vcc, 0x3000, v12
	s_nop 1
	v_addc_co_u32_e32 v13, vcc, 0, v13, vcc
	global_load_dword v166, v[12:13], off nt
	v_add_co_u32_e32 v12, vcc, 0x3000, v12
	s_nop 1
	v_addc_co_u32_e32 v13, vcc, 0, v13, vcc
	global_load_dword v167, v[12:13], off nt
	v_add_co_u32_e32 v12, vcc, 0x3000, v12
	s_nop 1
	v_addc_co_u32_e32 v13, vcc, 0, v13, vcc
	global_load_dword v168, v[12:13], off nt
	v_add_co_u32_e32 v12, vcc, 0x3000, v12
	s_nop 1
	v_addc_co_u32_e32 v13, vcc, 0, v13, vcc
	global_load_dword v169, v[12:13], off nt
	v_add_co_u32_e32 v12, vcc, 0x3000, v12
	s_nop 1
	v_addc_co_u32_e32 v13, vcc, 0, v13, vcc
	global_load_dword v170, v[12:13], off nt
	v_add_co_u32_e32 v12, vcc, 0x3000, v12
	s_nop 1
	v_addc_co_u32_e32 v13, vcc, 0, v13, vcc
	global_load_dword v171, v[12:13], off nt
	v_add_co_u32_e32 v12, vcc, 0x3000, v12
	s_nop 1
	v_addc_co_u32_e32 v13, vcc, 0, v13, vcc
	global_load_dword v172, v[12:13], off nt
	v_add_co_u32_e32 v12, vcc, 0x3000, v12
	s_nop 1
	v_addc_co_u32_e32 v13, vcc, 0, v13, vcc
	global_load_dword v173, v[12:13], off nt
	v_add_co_u32_e32 v12, vcc, 0x3000, v12
	s_nop 1
	v_addc_co_u32_e32 v13, vcc, 0, v13, vcc
	global_load_dword v174, v[12:13], off nt
	v_add_co_u32_e32 v12, vcc, 0x3000, v12
	s_nop 1
	v_addc_co_u32_e32 v13, vcc, 0, v13, vcc
	global_load_dword v175, v[12:13], off nt
	v_add_co_u32_e32 v12, vcc, 0x3000, v12
	s_nop 1
	v_addc_co_u32_e32 v13, vcc, 0, v13, vcc
	global_load_dword v176, v[12:13], off nt
	v_add_co_u32_e32 v12, vcc, 0x3000, v12
	s_nop 1
	v_addc_co_u32_e32 v13, vcc, 0, v13, vcc
	global_load_dword v177, v[12:13], off nt
	v_add_co_u32_e32 v12, vcc, 0x3000, v12
	s_nop 1
	v_addc_co_u32_e32 v13, vcc, 0, v13, vcc
	global_load_dword v178, v[12:13], off nt
	v_add_co_u32_e32 v12, vcc, 0x3000, v12
	s_nop 1
	v_addc_co_u32_e32 v13, vcc, 0, v13, vcc
	global_load_dword v179, v[12:13], off nt
	v_add_co_u32_e32 v12, vcc, 0x3000, v12
	s_nop 1
	v_addc_co_u32_e32 v13, vcc, 0, v13, vcc
	global_load_dword v180, v[12:13], off nt
	v_add_co_u32_e32 v12, vcc, 0x3000, v12
	s_nop 1
	v_addc_co_u32_e32 v13, vcc, 0, v13, vcc
	global_load_dword v181, v[12:13], off nt
	v_add_co_u32_e32 v12, vcc, 0x3000, v12
	s_nop 1
	v_addc_co_u32_e32 v13, vcc, 0, v13, vcc
	global_load_dword v182, v[12:13], off nt
	v_add_co_u32_e32 v12, vcc, 0x3000, v12
	s_nop 1
	v_addc_co_u32_e32 v13, vcc, 0, v13, vcc
	global_load_dword v183, v[12:13], off nt
	v_add_co_u32_e32 v12, vcc, 0x3000, v12
	s_nop 1
	v_addc_co_u32_e32 v13, vcc, 0, v13, vcc
	global_load_dword v184, v[12:13], off nt
	v_add_co_u32_e32 v12, vcc, 0x3000, v12
	s_nop 1
	v_addc_co_u32_e32 v13, vcc, 0, v13, vcc
	global_load_dword v185, v[12:13], off nt
	v_add_co_u32_e32 v12, vcc, 0x3000, v12
	s_nop 1
	v_addc_co_u32_e32 v13, vcc, 0, v13, vcc
	global_load_dword v186, v[12:13], off nt
	v_add_co_u32_e32 v12, vcc, 0x3000, v12
	s_nop 1
	v_addc_co_u32_e32 v13, vcc, 0, v13, vcc
	global_load_dword v187, v[12:13], off nt
	v_add_co_u32_e32 v12, vcc, 0x3000, v12
	s_nop 1
	v_addc_co_u32_e32 v13, vcc, 0, v13, vcc
	global_load_dword v188, v[12:13], off nt
	v_add_co_u32_e32 v12, vcc, 0x3000, v12
	s_nop 1
	v_addc_co_u32_e32 v13, vcc, 0, v13, vcc
	global_load_dword v189, v[12:13], off nt
	v_add_co_u32_e32 v12, vcc, 0x3000, v12
	s_nop 1
	v_addc_co_u32_e32 v13, vcc, 0, v13, vcc
	global_load_dword v190, v[12:13], off nt
	v_add_co_u32_e32 v12, vcc, 0x3000, v12
	s_nop 1
	v_addc_co_u32_e32 v13, vcc, 0, v13, vcc
	global_load_dword v191, v[12:13], off nt
	v_add_co_u32_e32 v12, vcc, 0x3000, v12
	s_nop 1
	v_addc_co_u32_e32 v13, vcc, 0, v13, vcc
	global_load_dword v192, v[12:13], off nt
	v_add_co_u32_e32 v12, vcc, 0x3000, v12
	s_nop 1
	v_addc_co_u32_e32 v13, vcc, 0, v13, vcc
	global_load_dword v193, v[12:13], off nt
	v_add_co_u32_e32 v12, vcc, 0x3000, v12
	s_nop 1
	v_addc_co_u32_e32 v13, vcc, 0, v13, vcc
	global_load_dword v194, v[12:13], off nt
	v_add_co_u32_e32 v12, vcc, 0x3000, v12
	s_nop 1
	v_addc_co_u32_e32 v13, vcc, 0, v13, vcc
	global_load_dword v195, v[12:13], off nt
	v_readlane_b32 s42, v0, 0
	v_readlane_b32 s43, v22, 0
	v_readlane_b32 s52, v23, 0
	v_readlane_b32 s53, v24, 0
	v_readlane_b32 s56, v25, 0
	s_waitcnt vmcnt(63)
	v_pk_fma_f32 v[10:11], v[132:133], s[42:43], v[10:11] op_sel_hi:[0,1,1]
	v_pk_fma_f32 v[8:9], v[132:133], s[52:53], v[8:9] op_sel_hi:[0,1,1]
	v_fmac_f32_e32 v21, s56, v132
	v_readlane_b32 s42, v0, 1
	v_readlane_b32 s43, v22, 1
	v_readlane_b32 s52, v23, 1
	v_readlane_b32 s53, v24, 1
	v_readlane_b32 s56, v25, 1
	s_waitcnt vmcnt(62)
	v_pk_fma_f32 v[10:11], v[132:133], s[42:43], v[10:11] op_sel:[1,0,0] op_sel_hi:[1,1,1]
	v_pk_fma_f32 v[8:9], v[132:133], s[52:53], v[8:9] op_sel:[1,0,0] op_sel_hi:[1,1,1]
	v_fmac_f32_e32 v21, s56, v133
	v_readlane_b32 s42, v0, 2
	v_readlane_b32 s43, v22, 2
	v_readlane_b32 s52, v23, 2
	v_readlane_b32 s53, v24, 2
	v_readlane_b32 s56, v25, 2
	s_waitcnt vmcnt(61)
	v_pk_fma_f32 v[10:11], v[134:135], s[42:43], v[10:11] op_sel_hi:[0,1,1]
	v_pk_fma_f32 v[8:9], v[134:135], s[52:53], v[8:9] op_sel_hi:[0,1,1]
	v_fmac_f32_e32 v21, s56, v134
	v_readlane_b32 s42, v0, 3
	v_readlane_b32 s43, v22, 3
	v_readlane_b32 s52, v23, 3
	v_readlane_b32 s53, v24, 3
	v_readlane_b32 s56, v25, 3
	s_waitcnt vmcnt(60)
	v_pk_fma_f32 v[10:11], v[134:135], s[42:43], v[10:11] op_sel:[1,0,0] op_sel_hi:[1,1,1]
	v_pk_fma_f32 v[8:9], v[134:135], s[52:53], v[8:9] op_sel:[1,0,0] op_sel_hi:[1,1,1]
	v_fmac_f32_e32 v21, s56, v135
	v_readlane_b32 s42, v0, 4
	v_readlane_b32 s43, v22, 4
	v_readlane_b32 s52, v23, 4
	v_readlane_b32 s53, v24, 4
	v_readlane_b32 s56, v25, 4
	s_waitcnt vmcnt(59)
	v_pk_fma_f32 v[10:11], v[136:137], s[42:43], v[10:11] op_sel_hi:[0,1,1]
	v_pk_fma_f32 v[8:9], v[136:137], s[52:53], v[8:9] op_sel_hi:[0,1,1]
	v_fmac_f32_e32 v21, s56, v136
	v_readlane_b32 s42, v0, 5
	v_readlane_b32 s43, v22, 5
	v_readlane_b32 s52, v23, 5
	v_readlane_b32 s53, v24, 5
	v_readlane_b32 s56, v25, 5
	s_waitcnt vmcnt(58)
	v_pk_fma_f32 v[10:11], v[136:137], s[42:43], v[10:11] op_sel:[1,0,0] op_sel_hi:[1,1,1]
	v_pk_fma_f32 v[8:9], v[136:137], s[52:53], v[8:9] op_sel:[1,0,0] op_sel_hi:[1,1,1]
	v_fmac_f32_e32 v21, s56, v137
	v_readlane_b32 s42, v0, 6
	v_readlane_b32 s43, v22, 6
	v_readlane_b32 s52, v23, 6
	v_readlane_b32 s53, v24, 6
	v_readlane_b32 s56, v25, 6
	s_waitcnt vmcnt(57)
	v_pk_fma_f32 v[10:11], v[138:139], s[42:43], v[10:11] op_sel_hi:[0,1,1]
	v_pk_fma_f32 v[8:9], v[138:139], s[52:53], v[8:9] op_sel_hi:[0,1,1]
	v_fmac_f32_e32 v21, s56, v138
	v_readlane_b32 s42, v0, 7
	v_readlane_b32 s43, v22, 7
	v_readlane_b32 s52, v23, 7
	v_readlane_b32 s53, v24, 7
	v_readlane_b32 s56, v25, 7
	s_waitcnt vmcnt(56)
	v_pk_fma_f32 v[10:11], v[138:139], s[42:43], v[10:11] op_sel:[1,0,0] op_sel_hi:[1,1,1]
	v_pk_fma_f32 v[8:9], v[138:139], s[52:53], v[8:9] op_sel:[1,0,0] op_sel_hi:[1,1,1]
	v_fmac_f32_e32 v21, s56, v139
	v_readlane_b32 s42, v0, 8
	v_readlane_b32 s43, v22, 8
	v_readlane_b32 s52, v23, 8
	v_readlane_b32 s53, v24, 8
	v_readlane_b32 s56, v25, 8
	s_waitcnt vmcnt(55)
	v_pk_fma_f32 v[10:11], v[140:141], s[42:43], v[10:11] op_sel_hi:[0,1,1]
	v_pk_fma_f32 v[8:9], v[140:141], s[52:53], v[8:9] op_sel_hi:[0,1,1]
	v_fmac_f32_e32 v21, s56, v140
	v_readlane_b32 s42, v0, 9
	v_readlane_b32 s43, v22, 9
	v_readlane_b32 s52, v23, 9
	v_readlane_b32 s53, v24, 9
	v_readlane_b32 s56, v25, 9
	s_waitcnt vmcnt(54)
	v_pk_fma_f32 v[10:11], v[140:141], s[42:43], v[10:11] op_sel:[1,0,0] op_sel_hi:[1,1,1]
	v_pk_fma_f32 v[8:9], v[140:141], s[52:53], v[8:9] op_sel:[1,0,0] op_sel_hi:[1,1,1]
	v_fmac_f32_e32 v21, s56, v141
	v_readlane_b32 s42, v0, 10
	v_readlane_b32 s43, v22, 10
	v_readlane_b32 s52, v23, 10
	v_readlane_b32 s53, v24, 10
	v_readlane_b32 s56, v25, 10
	s_waitcnt vmcnt(53)
	v_pk_fma_f32 v[10:11], v[142:143], s[42:43], v[10:11] op_sel_hi:[0,1,1]
	v_pk_fma_f32 v[8:9], v[142:143], s[52:53], v[8:9] op_sel_hi:[0,1,1]
	v_fmac_f32_e32 v21, s56, v142
	v_readlane_b32 s42, v0, 11
	v_readlane_b32 s43, v22, 11
	v_readlane_b32 s52, v23, 11
	v_readlane_b32 s53, v24, 11
	v_readlane_b32 s56, v25, 11
	s_waitcnt vmcnt(52)
	v_pk_fma_f32 v[10:11], v[142:143], s[42:43], v[10:11] op_sel:[1,0,0] op_sel_hi:[1,1,1]
	v_pk_fma_f32 v[8:9], v[142:143], s[52:53], v[8:9] op_sel:[1,0,0] op_sel_hi:[1,1,1]
	v_fmac_f32_e32 v21, s56, v143
	v_readlane_b32 s42, v0, 12
	v_readlane_b32 s43, v22, 12
	v_readlane_b32 s52, v23, 12
	v_readlane_b32 s53, v24, 12
	v_readlane_b32 s56, v25, 12
	s_waitcnt vmcnt(51)
	v_pk_fma_f32 v[10:11], v[144:145], s[42:43], v[10:11] op_sel_hi:[0,1,1]
	v_pk_fma_f32 v[8:9], v[144:145], s[52:53], v[8:9] op_sel_hi:[0,1,1]
	v_fmac_f32_e32 v21, s56, v144
	v_readlane_b32 s42, v0, 13
	v_readlane_b32 s43, v22, 13
	v_readlane_b32 s52, v23, 13
	v_readlane_b32 s53, v24, 13
	v_readlane_b32 s56, v25, 13
	s_waitcnt vmcnt(50)
	v_pk_fma_f32 v[10:11], v[144:145], s[42:43], v[10:11] op_sel:[1,0,0] op_sel_hi:[1,1,1]
	v_pk_fma_f32 v[8:9], v[144:145], s[52:53], v[8:9] op_sel:[1,0,0] op_sel_hi:[1,1,1]
	v_fmac_f32_e32 v21, s56, v145
	v_readlane_b32 s42, v0, 14
	v_readlane_b32 s43, v22, 14
	v_readlane_b32 s52, v23, 14
	v_readlane_b32 s53, v24, 14
	v_readlane_b32 s56, v25, 14
	s_waitcnt vmcnt(49)
	v_pk_fma_f32 v[10:11], v[146:147], s[42:43], v[10:11] op_sel_hi:[0,1,1]
	v_pk_fma_f32 v[8:9], v[146:147], s[52:53], v[8:9] op_sel_hi:[0,1,1]
	v_fmac_f32_e32 v21, s56, v146
	v_readlane_b32 s42, v0, 15
	v_readlane_b32 s43, v22, 15
	v_readlane_b32 s52, v23, 15
	v_readlane_b32 s53, v24, 15
	v_readlane_b32 s56, v25, 15
	s_waitcnt vmcnt(48)
	v_pk_fma_f32 v[10:11], v[146:147], s[42:43], v[10:11] op_sel:[1,0,0] op_sel_hi:[1,1,1]
	v_pk_fma_f32 v[8:9], v[146:147], s[52:53], v[8:9] op_sel:[1,0,0] op_sel_hi:[1,1,1]
	v_fmac_f32_e32 v21, s56, v147
	v_readlane_b32 s42, v0, 16
	v_readlane_b32 s43, v22, 16
	v_readlane_b32 s52, v23, 16
	v_readlane_b32 s53, v24, 16
	v_readlane_b32 s56, v25, 16
	s_waitcnt vmcnt(47)
	v_pk_fma_f32 v[10:11], v[148:149], s[42:43], v[10:11] op_sel_hi:[0,1,1]
	v_pk_fma_f32 v[8:9], v[148:149], s[52:53], v[8:9] op_sel_hi:[0,1,1]
	v_fmac_f32_e32 v21, s56, v148
	v_readlane_b32 s42, v0, 17
	v_readlane_b32 s43, v22, 17
	v_readlane_b32 s52, v23, 17
	v_readlane_b32 s53, v24, 17
	v_readlane_b32 s56, v25, 17
	s_waitcnt vmcnt(46)
	v_pk_fma_f32 v[10:11], v[148:149], s[42:43], v[10:11] op_sel:[1,0,0] op_sel_hi:[1,1,1]
	v_pk_fma_f32 v[8:9], v[148:149], s[52:53], v[8:9] op_sel:[1,0,0] op_sel_hi:[1,1,1]
	v_fmac_f32_e32 v21, s56, v149
	v_readlane_b32 s42, v0, 18
	v_readlane_b32 s43, v22, 18
	v_readlane_b32 s52, v23, 18
	v_readlane_b32 s53, v24, 18
	v_readlane_b32 s56, v25, 18
	s_waitcnt vmcnt(45)
	v_pk_fma_f32 v[10:11], v[150:151], s[42:43], v[10:11] op_sel_hi:[0,1,1]
	v_pk_fma_f32 v[8:9], v[150:151], s[52:53], v[8:9] op_sel_hi:[0,1,1]
	v_fmac_f32_e32 v21, s56, v150
	v_readlane_b32 s42, v0, 19
	v_readlane_b32 s43, v22, 19
	v_readlane_b32 s52, v23, 19
	v_readlane_b32 s53, v24, 19
	v_readlane_b32 s56, v25, 19
	s_waitcnt vmcnt(44)
	v_pk_fma_f32 v[10:11], v[150:151], s[42:43], v[10:11] op_sel:[1,0,0] op_sel_hi:[1,1,1]
	v_pk_fma_f32 v[8:9], v[150:151], s[52:53], v[8:9] op_sel:[1,0,0] op_sel_hi:[1,1,1]
	v_fmac_f32_e32 v21, s56, v151
	v_readlane_b32 s42, v0, 20
	v_readlane_b32 s43, v22, 20
	v_readlane_b32 s52, v23, 20
	v_readlane_b32 s53, v24, 20
	v_readlane_b32 s56, v25, 20
	s_waitcnt vmcnt(43)
	v_pk_fma_f32 v[10:11], v[152:153], s[42:43], v[10:11] op_sel_hi:[0,1,1]
	v_pk_fma_f32 v[8:9], v[152:153], s[52:53], v[8:9] op_sel_hi:[0,1,1]
	v_fmac_f32_e32 v21, s56, v152
	v_readlane_b32 s42, v0, 21
	v_readlane_b32 s43, v22, 21
	v_readlane_b32 s52, v23, 21
	v_readlane_b32 s53, v24, 21
	v_readlane_b32 s56, v25, 21
	s_waitcnt vmcnt(42)
	v_pk_fma_f32 v[10:11], v[152:153], s[42:43], v[10:11] op_sel:[1,0,0] op_sel_hi:[1,1,1]
	v_pk_fma_f32 v[8:9], v[152:153], s[52:53], v[8:9] op_sel:[1,0,0] op_sel_hi:[1,1,1]
	v_fmac_f32_e32 v21, s56, v153
	v_readlane_b32 s42, v0, 22
	v_readlane_b32 s43, v22, 22
	v_readlane_b32 s52, v23, 22
	v_readlane_b32 s53, v24, 22
	v_readlane_b32 s56, v25, 22
	s_waitcnt vmcnt(41)
	v_pk_fma_f32 v[10:11], v[154:155], s[42:43], v[10:11] op_sel_hi:[0,1,1]
	v_pk_fma_f32 v[8:9], v[154:155], s[52:53], v[8:9] op_sel_hi:[0,1,1]
	v_fmac_f32_e32 v21, s56, v154
	v_readlane_b32 s42, v0, 23
	v_readlane_b32 s43, v22, 23
	v_readlane_b32 s52, v23, 23
	v_readlane_b32 s53, v24, 23
	v_readlane_b32 s56, v25, 23
	s_waitcnt vmcnt(40)
	v_pk_fma_f32 v[10:11], v[154:155], s[42:43], v[10:11] op_sel:[1,0,0] op_sel_hi:[1,1,1]
	v_pk_fma_f32 v[8:9], v[154:155], s[52:53], v[8:9] op_sel:[1,0,0] op_sel_hi:[1,1,1]
	v_fmac_f32_e32 v21, s56, v155
	v_readlane_b32 s42, v0, 24
	v_readlane_b32 s43, v22, 24
	v_readlane_b32 s52, v23, 24
	v_readlane_b32 s53, v24, 24
	v_readlane_b32 s56, v25, 24
	s_waitcnt vmcnt(39)
	v_pk_fma_f32 v[10:11], v[156:157], s[42:43], v[10:11] op_sel_hi:[0,1,1]
	v_pk_fma_f32 v[8:9], v[156:157], s[52:53], v[8:9] op_sel_hi:[0,1,1]
	v_fmac_f32_e32 v21, s56, v156
	v_readlane_b32 s42, v0, 25
	v_readlane_b32 s43, v22, 25
	v_readlane_b32 s52, v23, 25
	v_readlane_b32 s53, v24, 25
	v_readlane_b32 s56, v25, 25
	s_waitcnt vmcnt(38)
	v_pk_fma_f32 v[10:11], v[156:157], s[42:43], v[10:11] op_sel:[1,0,0] op_sel_hi:[1,1,1]
	v_pk_fma_f32 v[8:9], v[156:157], s[52:53], v[8:9] op_sel:[1,0,0] op_sel_hi:[1,1,1]
	v_fmac_f32_e32 v21, s56, v157
	v_readlane_b32 s42, v0, 26
	v_readlane_b32 s43, v22, 26
	v_readlane_b32 s52, v23, 26
	v_readlane_b32 s53, v24, 26
	v_readlane_b32 s56, v25, 26
	s_waitcnt vmcnt(37)
	v_pk_fma_f32 v[10:11], v[158:159], s[42:43], v[10:11] op_sel_hi:[0,1,1]
	v_pk_fma_f32 v[8:9], v[158:159], s[52:53], v[8:9] op_sel_hi:[0,1,1]
	v_fmac_f32_e32 v21, s56, v158
	v_readlane_b32 s42, v0, 27
	v_readlane_b32 s43, v22, 27
	v_readlane_b32 s52, v23, 27
	v_readlane_b32 s53, v24, 27
	v_readlane_b32 s56, v25, 27
	s_waitcnt vmcnt(36)
	v_pk_fma_f32 v[10:11], v[158:159], s[42:43], v[10:11] op_sel:[1,0,0] op_sel_hi:[1,1,1]
	v_pk_fma_f32 v[8:9], v[158:159], s[52:53], v[8:9] op_sel:[1,0,0] op_sel_hi:[1,1,1]
	v_fmac_f32_e32 v21, s56, v159
	v_readlane_b32 s42, v0, 28
	v_readlane_b32 s43, v22, 28
	v_readlane_b32 s52, v23, 28
	v_readlane_b32 s53, v24, 28
	v_readlane_b32 s56, v25, 28
	s_waitcnt vmcnt(35)
	v_pk_fma_f32 v[10:11], v[160:161], s[42:43], v[10:11] op_sel_hi:[0,1,1]
	v_pk_fma_f32 v[8:9], v[160:161], s[52:53], v[8:9] op_sel_hi:[0,1,1]
	v_fmac_f32_e32 v21, s56, v160
	v_readlane_b32 s42, v0, 29
	v_readlane_b32 s43, v22, 29
	v_readlane_b32 s52, v23, 29
	v_readlane_b32 s53, v24, 29
	v_readlane_b32 s56, v25, 29
	s_waitcnt vmcnt(34)
	v_pk_fma_f32 v[10:11], v[160:161], s[42:43], v[10:11] op_sel:[1,0,0] op_sel_hi:[1,1,1]
	v_pk_fma_f32 v[8:9], v[160:161], s[52:53], v[8:9] op_sel:[1,0,0] op_sel_hi:[1,1,1]
	v_fmac_f32_e32 v21, s56, v161
	v_readlane_b32 s42, v0, 30
	v_readlane_b32 s43, v22, 30
	v_readlane_b32 s52, v23, 30
	v_readlane_b32 s53, v24, 30
	v_readlane_b32 s56, v25, 30
	s_waitcnt vmcnt(33)
	v_pk_fma_f32 v[10:11], v[162:163], s[42:43], v[10:11] op_sel_hi:[0,1,1]
	v_pk_fma_f32 v[8:9], v[162:163], s[52:53], v[8:9] op_sel_hi:[0,1,1]
	v_fmac_f32_e32 v21, s56, v162
	v_readlane_b32 s42, v0, 31
	v_readlane_b32 s43, v22, 31
	v_readlane_b32 s52, v23, 31
	v_readlane_b32 s53, v24, 31
	v_readlane_b32 s56, v25, 31
	s_waitcnt vmcnt(32)
	v_pk_fma_f32 v[10:11], v[162:163], s[42:43], v[10:11] op_sel:[1,0,0] op_sel_hi:[1,1,1]
	v_pk_fma_f32 v[8:9], v[162:163], s[52:53], v[8:9] op_sel:[1,0,0] op_sel_hi:[1,1,1]
	v_fmac_f32_e32 v21, s56, v163
	v_readlane_b32 s42, v0, 32
	v_readlane_b32 s43, v22, 32
	v_readlane_b32 s52, v23, 32
	v_readlane_b32 s53, v24, 32
	v_readlane_b32 s56, v25, 32
	s_waitcnt vmcnt(31)
	v_pk_fma_f32 v[10:11], v[164:165], s[42:43], v[10:11] op_sel_hi:[0,1,1]
	v_pk_fma_f32 v[8:9], v[164:165], s[52:53], v[8:9] op_sel_hi:[0,1,1]
	v_fmac_f32_e32 v21, s56, v164
	v_readlane_b32 s42, v0, 33
	v_readlane_b32 s43, v22, 33
	v_readlane_b32 s52, v23, 33
	v_readlane_b32 s53, v24, 33
	v_readlane_b32 s56, v25, 33
	s_waitcnt vmcnt(30)
	v_pk_fma_f32 v[10:11], v[164:165], s[42:43], v[10:11] op_sel:[1,0,0] op_sel_hi:[1,1,1]
	v_pk_fma_f32 v[8:9], v[164:165], s[52:53], v[8:9] op_sel:[1,0,0] op_sel_hi:[1,1,1]
	v_fmac_f32_e32 v21, s56, v165
	v_readlane_b32 s42, v0, 34
	v_readlane_b32 s43, v22, 34
	v_readlane_b32 s52, v23, 34
	v_readlane_b32 s53, v24, 34
	v_readlane_b32 s56, v25, 34
	s_waitcnt vmcnt(29)
	v_pk_fma_f32 v[10:11], v[166:167], s[42:43], v[10:11] op_sel_hi:[0,1,1]
	v_pk_fma_f32 v[8:9], v[166:167], s[52:53], v[8:9] op_sel_hi:[0,1,1]
	v_fmac_f32_e32 v21, s56, v166
	v_readlane_b32 s42, v0, 35
	v_readlane_b32 s43, v22, 35
	v_readlane_b32 s52, v23, 35
	v_readlane_b32 s53, v24, 35
	v_readlane_b32 s56, v25, 35
	s_waitcnt vmcnt(28)
	v_pk_fma_f32 v[10:11], v[166:167], s[42:43], v[10:11] op_sel:[1,0,0] op_sel_hi:[1,1,1]
	v_pk_fma_f32 v[8:9], v[166:167], s[52:53], v[8:9] op_sel:[1,0,0] op_sel_hi:[1,1,1]
	v_fmac_f32_e32 v21, s56, v167
	v_readlane_b32 s42, v0, 36
	v_readlane_b32 s43, v22, 36
	v_readlane_b32 s52, v23, 36
	v_readlane_b32 s53, v24, 36
	v_readlane_b32 s56, v25, 36
	s_waitcnt vmcnt(27)
	v_pk_fma_f32 v[10:11], v[168:169], s[42:43], v[10:11] op_sel_hi:[0,1,1]
	v_pk_fma_f32 v[8:9], v[168:169], s[52:53], v[8:9] op_sel_hi:[0,1,1]
	v_fmac_f32_e32 v21, s56, v168
	v_readlane_b32 s42, v0, 37
	v_readlane_b32 s43, v22, 37
	v_readlane_b32 s52, v23, 37
	v_readlane_b32 s53, v24, 37
	v_readlane_b32 s56, v25, 37
	s_waitcnt vmcnt(26)
	v_pk_fma_f32 v[10:11], v[168:169], s[42:43], v[10:11] op_sel:[1,0,0] op_sel_hi:[1,1,1]
	v_pk_fma_f32 v[8:9], v[168:169], s[52:53], v[8:9] op_sel:[1,0,0] op_sel_hi:[1,1,1]
	v_fmac_f32_e32 v21, s56, v169
	v_readlane_b32 s42, v0, 38
	v_readlane_b32 s43, v22, 38
	v_readlane_b32 s52, v23, 38
	v_readlane_b32 s53, v24, 38
	v_readlane_b32 s56, v25, 38
	s_waitcnt vmcnt(25)
	v_pk_fma_f32 v[10:11], v[170:171], s[42:43], v[10:11] op_sel_hi:[0,1,1]
	v_pk_fma_f32 v[8:9], v[170:171], s[52:53], v[8:9] op_sel_hi:[0,1,1]
	v_fmac_f32_e32 v21, s56, v170
	v_readlane_b32 s42, v0, 39
	v_readlane_b32 s43, v22, 39
	v_readlane_b32 s52, v23, 39
	v_readlane_b32 s53, v24, 39
	v_readlane_b32 s56, v25, 39
	s_waitcnt vmcnt(24)
	v_pk_fma_f32 v[10:11], v[170:171], s[42:43], v[10:11] op_sel:[1,0,0] op_sel_hi:[1,1,1]
	v_pk_fma_f32 v[8:9], v[170:171], s[52:53], v[8:9] op_sel:[1,0,0] op_sel_hi:[1,1,1]
	v_fmac_f32_e32 v21, s56, v171
	v_readlane_b32 s42, v0, 40
	v_readlane_b32 s43, v22, 40
	v_readlane_b32 s52, v23, 40
	v_readlane_b32 s53, v24, 40
	v_readlane_b32 s56, v25, 40
	s_waitcnt vmcnt(23)
	v_pk_fma_f32 v[10:11], v[172:173], s[42:43], v[10:11] op_sel_hi:[0,1,1]
	v_pk_fma_f32 v[8:9], v[172:173], s[52:53], v[8:9] op_sel_hi:[0,1,1]
	v_fmac_f32_e32 v21, s56, v172
	v_readlane_b32 s42, v0, 41
	v_readlane_b32 s43, v22, 41
	v_readlane_b32 s52, v23, 41
	v_readlane_b32 s53, v24, 41
	v_readlane_b32 s56, v25, 41
	s_waitcnt vmcnt(22)
	v_pk_fma_f32 v[10:11], v[172:173], s[42:43], v[10:11] op_sel:[1,0,0] op_sel_hi:[1,1,1]
	v_pk_fma_f32 v[8:9], v[172:173], s[52:53], v[8:9] op_sel:[1,0,0] op_sel_hi:[1,1,1]
	v_fmac_f32_e32 v21, s56, v173
	v_readlane_b32 s42, v0, 42
	v_readlane_b32 s43, v22, 42
	v_readlane_b32 s52, v23, 42
	v_readlane_b32 s53, v24, 42
	v_readlane_b32 s56, v25, 42
	s_waitcnt vmcnt(21)
	v_pk_fma_f32 v[10:11], v[174:175], s[42:43], v[10:11] op_sel_hi:[0,1,1]
	v_pk_fma_f32 v[8:9], v[174:175], s[52:53], v[8:9] op_sel_hi:[0,1,1]
	v_fmac_f32_e32 v21, s56, v174
	v_readlane_b32 s42, v0, 43
	v_readlane_b32 s43, v22, 43
	v_readlane_b32 s52, v23, 43
	v_readlane_b32 s53, v24, 43
	v_readlane_b32 s56, v25, 43
	s_waitcnt vmcnt(20)
	v_pk_fma_f32 v[10:11], v[174:175], s[42:43], v[10:11] op_sel:[1,0,0] op_sel_hi:[1,1,1]
	v_pk_fma_f32 v[8:9], v[174:175], s[52:53], v[8:9] op_sel:[1,0,0] op_sel_hi:[1,1,1]
	v_fmac_f32_e32 v21, s56, v175
	v_readlane_b32 s42, v0, 44
	v_readlane_b32 s43, v22, 44
	v_readlane_b32 s52, v23, 44
	v_readlane_b32 s53, v24, 44
	v_readlane_b32 s56, v25, 44
	s_waitcnt vmcnt(19)
	v_pk_fma_f32 v[10:11], v[176:177], s[42:43], v[10:11] op_sel_hi:[0,1,1]
	v_pk_fma_f32 v[8:9], v[176:177], s[52:53], v[8:9] op_sel_hi:[0,1,1]
	v_fmac_f32_e32 v21, s56, v176
	v_readlane_b32 s42, v0, 45
	v_readlane_b32 s43, v22, 45
	v_readlane_b32 s52, v23, 45
	v_readlane_b32 s53, v24, 45
	v_readlane_b32 s56, v25, 45
	s_waitcnt vmcnt(18)
	v_pk_fma_f32 v[10:11], v[176:177], s[42:43], v[10:11] op_sel:[1,0,0] op_sel_hi:[1,1,1]
	v_pk_fma_f32 v[8:9], v[176:177], s[52:53], v[8:9] op_sel:[1,0,0] op_sel_hi:[1,1,1]
	v_fmac_f32_e32 v21, s56, v177
	v_readlane_b32 s42, v0, 46
	v_readlane_b32 s43, v22, 46
	v_readlane_b32 s52, v23, 46
	v_readlane_b32 s53, v24, 46
	v_readlane_b32 s56, v25, 46
	s_waitcnt vmcnt(17)
	v_pk_fma_f32 v[10:11], v[178:179], s[42:43], v[10:11] op_sel_hi:[0,1,1]
	v_pk_fma_f32 v[8:9], v[178:179], s[52:53], v[8:9] op_sel_hi:[0,1,1]
	v_fmac_f32_e32 v21, s56, v178
	v_readlane_b32 s42, v0, 47
	v_readlane_b32 s43, v22, 47
	v_readlane_b32 s52, v23, 47
	v_readlane_b32 s53, v24, 47
	v_readlane_b32 s56, v25, 47
	s_waitcnt vmcnt(16)
	v_pk_fma_f32 v[10:11], v[178:179], s[42:43], v[10:11] op_sel:[1,0,0] op_sel_hi:[1,1,1]
	v_pk_fma_f32 v[8:9], v[178:179], s[52:53], v[8:9] op_sel:[1,0,0] op_sel_hi:[1,1,1]
	v_fmac_f32_e32 v21, s56, v179
	v_readlane_b32 s42, v0, 48
	v_readlane_b32 s43, v22, 48
	v_readlane_b32 s52, v23, 48
	v_readlane_b32 s53, v24, 48
	v_readlane_b32 s56, v25, 48
	s_waitcnt vmcnt(15)
	v_pk_fma_f32 v[10:11], v[180:181], s[42:43], v[10:11] op_sel_hi:[0,1,1]
	v_pk_fma_f32 v[8:9], v[180:181], s[52:53], v[8:9] op_sel_hi:[0,1,1]
	v_fmac_f32_e32 v21, s56, v180
	v_readlane_b32 s42, v0, 49
	v_readlane_b32 s43, v22, 49
	v_readlane_b32 s52, v23, 49
	v_readlane_b32 s53, v24, 49
	v_readlane_b32 s56, v25, 49
	s_waitcnt vmcnt(14)
	v_pk_fma_f32 v[10:11], v[180:181], s[42:43], v[10:11] op_sel:[1,0,0] op_sel_hi:[1,1,1]
	v_pk_fma_f32 v[8:9], v[180:181], s[52:53], v[8:9] op_sel:[1,0,0] op_sel_hi:[1,1,1]
	v_fmac_f32_e32 v21, s56, v181
	v_readlane_b32 s42, v0, 50
	v_readlane_b32 s43, v22, 50
	v_readlane_b32 s52, v23, 50
	v_readlane_b32 s53, v24, 50
	v_readlane_b32 s56, v25, 50
	s_waitcnt vmcnt(13)
	v_pk_fma_f32 v[10:11], v[182:183], s[42:43], v[10:11] op_sel_hi:[0,1,1]
	v_pk_fma_f32 v[8:9], v[182:183], s[52:53], v[8:9] op_sel_hi:[0,1,1]
	v_fmac_f32_e32 v21, s56, v182
	v_readlane_b32 s42, v0, 51
	v_readlane_b32 s43, v22, 51
	v_readlane_b32 s52, v23, 51
	v_readlane_b32 s53, v24, 51
	v_readlane_b32 s56, v25, 51
	s_waitcnt vmcnt(12)
	v_pk_fma_f32 v[10:11], v[182:183], s[42:43], v[10:11] op_sel:[1,0,0] op_sel_hi:[1,1,1]
	v_pk_fma_f32 v[8:9], v[182:183], s[52:53], v[8:9] op_sel:[1,0,0] op_sel_hi:[1,1,1]
	v_fmac_f32_e32 v21, s56, v183
	v_readlane_b32 s42, v0, 52
	v_readlane_b32 s43, v22, 52
	v_readlane_b32 s52, v23, 52
	v_readlane_b32 s53, v24, 52
	v_readlane_b32 s56, v25, 52
	s_waitcnt vmcnt(11)
	v_pk_fma_f32 v[10:11], v[184:185], s[42:43], v[10:11] op_sel_hi:[0,1,1]
	v_pk_fma_f32 v[8:9], v[184:185], s[52:53], v[8:9] op_sel_hi:[0,1,1]
	v_fmac_f32_e32 v21, s56, v184
	v_readlane_b32 s42, v0, 53
	v_readlane_b32 s43, v22, 53
	v_readlane_b32 s52, v23, 53
	v_readlane_b32 s53, v24, 53
	v_readlane_b32 s56, v25, 53
	s_waitcnt vmcnt(10)
	v_pk_fma_f32 v[10:11], v[184:185], s[42:43], v[10:11] op_sel:[1,0,0] op_sel_hi:[1,1,1]
	v_pk_fma_f32 v[8:9], v[184:185], s[52:53], v[8:9] op_sel:[1,0,0] op_sel_hi:[1,1,1]
	v_fmac_f32_e32 v21, s56, v185
	v_readlane_b32 s42, v0, 54
	v_readlane_b32 s43, v22, 54
	v_readlane_b32 s52, v23, 54
	v_readlane_b32 s53, v24, 54
	v_readlane_b32 s56, v25, 54
	s_waitcnt vmcnt(9)
	v_pk_fma_f32 v[10:11], v[186:187], s[42:43], v[10:11] op_sel_hi:[0,1,1]
	v_pk_fma_f32 v[8:9], v[186:187], s[52:53], v[8:9] op_sel_hi:[0,1,1]
	v_fmac_f32_e32 v21, s56, v186
	v_readlane_b32 s42, v0, 55
	v_readlane_b32 s43, v22, 55
	v_readlane_b32 s52, v23, 55
	v_readlane_b32 s53, v24, 55
	v_readlane_b32 s56, v25, 55
	s_waitcnt vmcnt(8)
	v_pk_fma_f32 v[10:11], v[186:187], s[42:43], v[10:11] op_sel:[1,0,0] op_sel_hi:[1,1,1]
	v_pk_fma_f32 v[8:9], v[186:187], s[52:53], v[8:9] op_sel:[1,0,0] op_sel_hi:[1,1,1]
	v_fmac_f32_e32 v21, s56, v187
	v_readlane_b32 s42, v0, 56
	v_readlane_b32 s43, v22, 56
	v_readlane_b32 s52, v23, 56
	v_readlane_b32 s53, v24, 56
	v_readlane_b32 s56, v25, 56
	s_waitcnt vmcnt(7)
	v_pk_fma_f32 v[10:11], v[188:189], s[42:43], v[10:11] op_sel_hi:[0,1,1]
	v_pk_fma_f32 v[8:9], v[188:189], s[52:53], v[8:9] op_sel_hi:[0,1,1]
	v_fmac_f32_e32 v21, s56, v188
	v_readlane_b32 s42, v0, 57
	v_readlane_b32 s43, v22, 57
	v_readlane_b32 s52, v23, 57
	v_readlane_b32 s53, v24, 57
	v_readlane_b32 s56, v25, 57
	s_waitcnt vmcnt(6)
	v_pk_fma_f32 v[10:11], v[188:189], s[42:43], v[10:11] op_sel:[1,0,0] op_sel_hi:[1,1,1]
	v_pk_fma_f32 v[8:9], v[188:189], s[52:53], v[8:9] op_sel:[1,0,0] op_sel_hi:[1,1,1]
	v_fmac_f32_e32 v21, s56, v189
	v_readlane_b32 s42, v0, 58
	v_readlane_b32 s43, v22, 58
	v_readlane_b32 s52, v23, 58
	v_readlane_b32 s53, v24, 58
	v_readlane_b32 s56, v25, 58
	s_waitcnt vmcnt(5)
	v_pk_fma_f32 v[10:11], v[190:191], s[42:43], v[10:11] op_sel_hi:[0,1,1]
	v_pk_fma_f32 v[8:9], v[190:191], s[52:53], v[8:9] op_sel_hi:[0,1,1]
	v_fmac_f32_e32 v21, s56, v190
	v_readlane_b32 s42, v0, 59
	v_readlane_b32 s43, v22, 59
	v_readlane_b32 s52, v23, 59
	v_readlane_b32 s53, v24, 59
	v_readlane_b32 s56, v25, 59
	s_waitcnt vmcnt(4)
	v_pk_fma_f32 v[10:11], v[190:191], s[42:43], v[10:11] op_sel:[1,0,0] op_sel_hi:[1,1,1]
	v_pk_fma_f32 v[8:9], v[190:191], s[52:53], v[8:9] op_sel:[1,0,0] op_sel_hi:[1,1,1]
	v_fmac_f32_e32 v21, s56, v191
	v_readlane_b32 s42, v0, 60
	v_readlane_b32 s43, v22, 60
	v_readlane_b32 s52, v23, 60
	v_readlane_b32 s53, v24, 60
	v_readlane_b32 s56, v25, 60
	s_waitcnt vmcnt(3)
	v_pk_fma_f32 v[10:11], v[192:193], s[42:43], v[10:11] op_sel_hi:[0,1,1]
	v_pk_fma_f32 v[8:9], v[192:193], s[52:53], v[8:9] op_sel_hi:[0,1,1]
	v_fmac_f32_e32 v21, s56, v192
	v_readlane_b32 s42, v0, 61
	v_readlane_b32 s43, v22, 61
	v_readlane_b32 s52, v23, 61
	v_readlane_b32 s53, v24, 61
	v_readlane_b32 s56, v25, 61
	s_waitcnt vmcnt(2)
	v_pk_fma_f32 v[10:11], v[192:193], s[42:43], v[10:11] op_sel:[1,0,0] op_sel_hi:[1,1,1]
	v_pk_fma_f32 v[8:9], v[192:193], s[52:53], v[8:9] op_sel:[1,0,0] op_sel_hi:[1,1,1]
	v_fmac_f32_e32 v21, s56, v193
	v_readlane_b32 s42, v0, 62
	v_readlane_b32 s43, v22, 62
	v_readlane_b32 s52, v23, 62
	v_readlane_b32 s53, v24, 62
	v_readlane_b32 s56, v25, 62
	s_waitcnt vmcnt(1)
	v_pk_fma_f32 v[10:11], v[194:195], s[42:43], v[10:11] op_sel_hi:[0,1,1]
	v_pk_fma_f32 v[8:9], v[194:195], s[52:53], v[8:9] op_sel_hi:[0,1,1]
	v_fmac_f32_e32 v21, s56, v194
	v_readlane_b32 s42, v0, 63
	v_readlane_b32 s43, v22, 63
	v_readlane_b32 s52, v23, 63
	v_readlane_b32 s53, v24, 63
	v_readlane_b32 s56, v25, 63
	s_waitcnt vmcnt(0)
	v_pk_fma_f32 v[10:11], v[194:195], s[42:43], v[10:11] op_sel:[1,0,0] op_sel_hi:[1,1,1]
	v_pk_fma_f32 v[8:9], v[194:195], s[52:53], v[8:9] op_sel:[1,0,0] op_sel_hi:[1,1,1]
	v_fmac_f32_e32 v21, s56, v195
	s_mov_b32 s40, 64
	s_mov_b64 s[4:5], 0
	s_and_b64 vcc, exec, s[12:13]
	s_cbranch_vccz .LBB0_930
	v_lshlrev_b32_e32 v0, 3, v16
	v_and_b32_e32 v6, 0xffffffc0, v0
	v_ashrrev_i32_e32 v7, 31, v6
	v_lshl_add_u64 v[6:7], v[6:7], 2, v[2:3]
	v_add_co_u32_e32 v12, vcc, 0x3000, v6
	global_store_dword v[6:7], v10, off
	s_nop 0
	v_addc_co_u32_e32 v13, vcc, 0, v7, vcc
	v_add_co_u32_e32 v10, vcc, 0x6000, v6
	global_store_dword v[12:13], v11, off
	s_nop 0
	v_addc_co_u32_e32 v11, vcc, 0, v7, vcc
	global_store_dword v[10:11], v8, off
	v_add_co_u32_e32 v10, vcc, 0x9000, v6
	v_add_u32_e32 v16, s16, v16
	s_nop 0
	v_addc_co_u32_e32 v11, vcc, 0, v7, vcc
	v_add_co_u32_e32 v6, vcc, 0xc000, v6
	v_add_u32_e32 v18, s3, v18
	s_nop 0
	v_addc_co_u32_e32 v7, vcc, 0, v7, vcc
	v_cmp_lt_i32_e32 vcc, s67, v16
	s_or_b64 s[10:11], vcc, s[10:11]
	global_store_dword v[10:11], v9, off
	global_store_dword v[6:7], v21, off
	s_andn2_b64 exec, exec, s[10:11]
	s_cbranch_execnz .LBB0_929
